# 7.4 static priority raise: s_setprio 1 for waves 4-7 through the NSA phase, per-group setprio flips in the selected loop replaced by nops
# baseline (speedup 1.0000x reference)
; __device__ __forceinline__ void nsa_phase(LAS unsigned char* lds, const bf16_t* Q, const bf16_t* KVG, size_t kvg_stride, const bf16_t* kcc, const bf16_t* vcc, const float* G, bf16_t* cat,
;                                           int tid, int lane, int wave) {
;     ...
;     for (int u = blockIdx.x; u < 2048; u += gridDim.x) {
;         const int rnd = u >> 8, cc = u & 255, xq = cc & 7, bg = 4 * rnd + (xq >> 1), ii = (xq & 1) * 32 + (cc >> 3), iq = (rnd & 1) ? 63 - ii : ii;
;         const int b = bg >> 2, g = bg & 3, t0 = 128 * iq;
;         int lane_u; asm volatile("v_mbcnt_lo_u32_b32 %0, -1, 0\n\tv_mbcnt_hi_u32_b32 %0, -1, %0" : "=&v"(lane_u));
;         const int lr = lane_u & 15, q = lane_u >> 4;
;         const int t = t0 + 16 * wave + lr; const size_t rowu = (size_t)b * SEQ + t0; const unsigned tl = (unsigned)(16 * wave + lr);
.LBB0_947:
	s_cmp_lt_u32 s26, 64
	s_cbranch_scc1 .Lprio_skip
	s_setprio 1

; #define LAS __attribute__((address_space(3)))
; #define MFMA16(a, b, c) __builtin_amdgcn_mfma_f32_16x16x32_bf16((a), (b), (c), 0, 0, 0)
; __device__ __forceinline__ void sel_group(const LAS bf16_t* Kt, const LAS bf16_t* Vt, LAS float* S, const bf16x8 qB0, const bf16x8 qB1, int jc, int rc, bool valid, bool masked, int tw64, int lr, int q) {
;     LAS float* Srow = S + (jc * 3 + rc) * 68;
;     const float mref = Srow[65]; const bool st = Srow[66] != 0.f;
;     f32x4 acc[4];
; #pragma unroll
;     for (int dt = 0; dt < 4; ++dt) acc[dt] = *(const LAS f32x4*)(Srow + 16 * dt + 4 * q);
;     float lc = Srow[64];
;     const float nm = valid ? -mref : -1e30f;
;     const f32x4 c0 = (f32x4){nm, nm, nm, nm};
;     const LAS bf16_t* kbase = Kt + lr * 72 + 8 * q;
;     f32x4 s[4];
;     {
;         bf16x8 kf[2][2];
;         kf[0][0] = *(const LAS bf16x8*)(kbase); kf[0][1] = *(const LAS bf16x8*)(kbase + 32);
; #pragma unroll
;         for (int mt = 0; mt < 4; ++mt) {
;             if (mt < 3) { kf[(mt + 1) & 1][0] = *(const LAS bf16x8*)(kbase + 16 * (mt + 1) * 72); kf[(mt + 1) & 1][1] = *(const LAS bf16x8*)(kbase + 16 * (mt + 1) * 72 + 32); }
;             __builtin_amdgcn_sched_barrier(0);
;             __builtin_amdgcn_s_setprio(1); s[mt] = MFMA16(kf[mt & 1][0], qB0, c0); s[mt] = MFMA16(kf[mt & 1][1], qB1, s[mt]); __builtin_amdgcn_s_setprio(0);
;             __builtin_amdgcn_sched_barrier(0);
;         }
;     }
;     if (masked) {
;         const int hq = tw64 + jc - 4 * q;
; #pragma unroll
;         for (int mt = 0; mt < 4; ++mt)
; #pragma unroll
;             for (int i = 0; i < 4; ++i) s[mt][i] = ((16 * mt + i) <= hq) ? s[mt][i] : -1e30f;
.Lsp_gdone_loop:
	s_waitcnt lgkmcnt(0)
	s_cmp_eq_u32 s101, 1
	s_cselect_b64 s[2:3], -1, 0
	s_cmp_eq_u32 s45, s38
	s_cselect_b64 s[12:13], -1, 0
	v_add_u32_e32 v48, s6, v99
	v_add_u32_e32 v117, v48, v97
	v_cndmask_b32_e64 v48, 0, 1, s[12:13]
	v_add3_u32 v115, s6, v104, v114
	s_cmp_eq_u32 s10, 0
	v_cmp_ne_u32_e64 s[72:73], 1, v48
	s_barrier
	s_cbranch_scc1 .LBB0_1078
	v_mad_u64_u32 v[48:49], s[4:5], v120, 3, v[88:89]
	v_mul_lo_u32 v48, v48, s36
	v_add_u32_e32 v119, s49, v48
	v_add_u32_e32 v48, v119, v97
	ds_read_b96 v[84:86], v119 offset:46336
	ds_read_b128 v[174:177], v117
	ds_read_b128 v[178:181], v117 offset:64
	ds_read_b128 v[182:185], v117 offset:2304
	ds_read_b128 v[186:189], v117 offset:2368
	ds_read_b128 v[200:203], v117 offset:4608
	ds_read_b128 v[216:219], v117 offset:4672
	ds_read_b128 v[122:125], v117 offset:6912
	ds_read_b128 v[138:141], v117 offset:6976
	ds_read_b128 v[60:63], v48 offset:46080
	ds_read_b128 v[56:59], v48 offset:46144
	ds_read_b128 v[52:55], v48 offset:46208
	ds_read_b128 v[48:51], v48 offset:46272
	s_waitcnt lgkmcnt(12)
	v_cndmask_b32_e64 v126, v222, -v85, s[76:77]
	v_mov_b32_e32 v127, v126
	v_mov_b32_e32 v128, v126
	v_mov_b32_e32 v129, v126
	s_nop 0
	s_waitcnt lgkmcnt(11)
	v_mfma_f32_16x16x32_bf16 v[64:67], v[174:177], v[76:79], v[126:129]
	s_waitcnt lgkmcnt(10)
	v_mfma_f32_16x16x32_bf16 v[64:67], v[178:181], v[80:83], v[64:67]
	s_waitcnt lgkmcnt(9)
	v_mfma_f32_16x16x32_bf16 v[68:71], v[182:185], v[76:79], v[126:129]
	s_waitcnt lgkmcnt(8)
	v_mfma_f32_16x16x32_bf16 v[68:71], v[186:189], v[80:83], v[68:71]
	s_waitcnt lgkmcnt(7)
	v_mfma_f32_16x16x32_bf16 v[72:75], v[200:203], v[76:79], v[126:129]
	s_waitcnt lgkmcnt(6)
	v_mfma_f32_16x16x32_bf16 v[72:75], v[216:219], v[80:83], v[72:75]
	s_waitcnt lgkmcnt(5)
	v_mfma_f32_16x16x32_bf16 v[76:79], v[122:125], v[76:79], v[126:129]
	s_waitcnt lgkmcnt(4)
	v_mfma_f32_16x16x32_bf16 v[76:79], v[138:141], v[80:83], v[76:79]
	s_nop 0
	s_and_b64 vcc, exec, s[72:73]
	s_cbranch_vccnz .LBB0_1067
	v_add_u32_e32 v80, v120, v111
	v_cmp_lt_i32_e32 vcc, -1, v80
	s_nop 1
	v_cndmask_b32_e32 v64, v222, v64, vcc
	v_cmp_lt_i32_e32 vcc, 0, v80
	s_nop 1
	v_cndmask_b32_e32 v65, v222, v65, vcc
	v_cmp_lt_i32_e32 vcc, 1, v80
	s_nop 1
	v_cndmask_b32_e32 v66, v222, v66, vcc
	v_cmp_lt_i32_e32 vcc, 2, v80
	s_nop 1
	v_cndmask_b32_e32 v67, v222, v67, vcc
	v_cmp_lt_i32_e32 vcc, 15, v80
	s_nop 1
	v_cndmask_b32_e32 v68, v222, v68, vcc
	v_cmp_lt_i32_e32 vcc, 16, v80
	s_nop 1
	v_cndmask_b32_e32 v69, v222, v69, vcc
	v_cmp_lt_i32_e32 vcc, 17, v80
	s_nop 1
	v_cndmask_b32_e32 v70, v222, v70, vcc
	v_cmp_lt_i32_e32 vcc, 18, v80
	s_nop 1
	v_cndmask_b32_e32 v71, v222, v71, vcc
	v_cmp_lt_i32_e32 vcc, 31, v80
	s_nop 1
	v_cndmask_b32_e32 v72, v222, v72, vcc
	v_cmp_lt_i32_e32 vcc, 32, v80
	s_nop 1
	v_cndmask_b32_e32 v73, v222, v73, vcc
	v_cmp_lt_i32_e32 vcc, 33, v80
	s_nop 1
	v_cndmask_b32_e32 v74, v222, v74, vcc
	v_cmp_lt_i32_e32 vcc, 34, v80
	s_nop 1
	v_cndmask_b32_e32 v75, v222, v75, vcc
	v_cmp_lt_i32_e32 vcc, 47, v80
	s_nop 1
	v_cndmask_b32_e32 v76, v222, v76, vcc
	v_cmp_lt_i32_e32 vcc, 48, v80
	s_nop 1
	v_cndmask_b32_e32 v77, v222, v77, vcc
	v_cmp_lt_i32_e32 vcc, 49, v80
	s_nop 1
	v_cndmask_b32_e32 v78, v222, v78, vcc
	v_cmp_lt_i32_e32 vcc, 50, v80
	s_nop 1
	v_cndmask_b32_e32 v79, v222, v79, vcc

; #define LAS __attribute__((address_space(3)))
; #define MFMA16(a, b, c) __builtin_amdgcn_mfma_f32_16x16x32_bf16((a), (b), (c), 0, 0, 0)
; __device__ __forceinline__ void sel_group(const LAS bf16_t* Kt, const LAS bf16_t* Vt, LAS float* S, const bf16x8 qB0, const bf16x8 qB1, int jc, int rc, bool valid, bool masked, int tw64, int lr, int q) {
;     LAS float* Srow = S + (jc * 3 + rc) * 68;
;     const float mref = Srow[65]; const bool st = Srow[66] != 0.f;
;     f32x4 acc[4];
; #pragma unroll
;     for (int dt = 0; dt < 4; ++dt) acc[dt] = *(const LAS f32x4*)(Srow + 16 * dt + 4 * q);
;     float lc = Srow[64];
;     const float nm = valid ? -mref : -1e30f;
;     const f32x4 c0 = (f32x4){nm, nm, nm, nm};
;     const LAS bf16_t* kbase = Kt + lr * 72 + 8 * q;
;     f32x4 s[4];
;     {
;         bf16x8 kf[2][2];
;         kf[0][0] = *(const LAS bf16x8*)(kbase); kf[0][1] = *(const LAS bf16x8*)(kbase + 32);
; #pragma unroll
;         for (int mt = 0; mt < 4; ++mt) {
;             if (mt < 3) { kf[(mt + 1) & 1][0] = *(const LAS bf16x8*)(kbase + 16 * (mt + 1) * 72); kf[(mt + 1) & 1][1] = *(const LAS bf16x8*)(kbase + 16 * (mt + 1) * 72 + 32); }
;             __builtin_amdgcn_sched_barrier(0);
;             __builtin_amdgcn_s_setprio(1); s[mt] = MFMA16(kf[mt & 1][0], qB0, c0); s[mt] = MFMA16(kf[mt & 1][1], qB1, s[mt]); __builtin_amdgcn_s_setprio(0);
;             __builtin_amdgcn_sched_barrier(0);
;         }
;     }
;     if (masked) {
;         const int hq = tw64 + jc - 4 * q;
; #pragma unroll
;         for (int mt = 0; mt < 4; ++mt)
; #pragma unroll
;             for (int i = 0; i < 4; ++i) s[mt][i] = ((16 * mt + i) <= hq) ? s[mt][i] : -1e30f;
.LBB0_1078:
	s_cmp_lt_u32 s10, 6
	s_cbranch_scc1 .LBB0_1092
	v_mad_u64_u32 v[48:49], s[4:5], v118, 3, v[92:93]
	v_mul_lo_u32 v48, v48, s36
	v_add_u32_e32 v79, s49, v48
	v_add_u32_e32 v48, v79, v97
	ds_read_b96 v[76:78], v79 offset:46336
	ds_read_b128 v[80:83], v117 offset:6912
	ds_read_b128 v[132:135], v117 offset:6976
	ds_read_b128 v[60:63], v48 offset:46080
	ds_read_b128 v[56:59], v48 offset:46144
	ds_read_b128 v[52:55], v48 offset:46208
	ds_read_b128 v[48:51], v48 offset:46272
	s_waitcnt lgkmcnt(6)
	v_cndmask_b32_e64 v120, v222, -v77, s[74:75]
	v_mov_b32_e32 v121, v120
	v_mov_b32_e32 v122, v120
	v_mov_b32_e32 v123, v120
	s_nop 0
	s_nop 0
	v_mfma_f32_16x16x32_bf16 v[64:67], v[174:177], v[40:43], v[120:123]
	v_mfma_f32_16x16x32_bf16 v[64:67], v[178:181], v[44:47], v[64:67]
	v_mfma_f32_16x16x32_bf16 v[68:71], v[182:185], v[40:43], v[120:123]
	v_mfma_f32_16x16x32_bf16 v[68:71], v[186:189], v[44:47], v[68:71]
	v_mfma_f32_16x16x32_bf16 v[72:75], v[200:203], v[40:43], v[120:123]
	v_mfma_f32_16x16x32_bf16 v[72:75], v[216:219], v[44:47], v[72:75]
	s_waitcnt lgkmcnt(5)
	v_mfma_f32_16x16x32_bf16 v[40:43], v[80:83], v[40:43], v[120:123]
	s_waitcnt lgkmcnt(4)
	v_mfma_f32_16x16x32_bf16 v[40:43], v[132:135], v[44:47], v[40:43]
	s_nop 0
	s_and_b64 vcc, exec, s[72:73]
	s_cbranch_vccnz .LBB0_1081
	v_add_u32_e32 v44, v118, v111
	v_cmp_lt_i32_e32 vcc, -1, v44
	s_nop 1
	v_cndmask_b32_e32 v64, v222, v64, vcc
	v_cmp_lt_i32_e32 vcc, 0, v44
	s_nop 1
	v_cndmask_b32_e32 v65, v222, v65, vcc
	v_cmp_lt_i32_e32 vcc, 1, v44
	s_nop 1
	v_cndmask_b32_e32 v66, v222, v66, vcc
	v_cmp_lt_i32_e32 vcc, 2, v44
	s_nop 1
	v_cndmask_b32_e32 v67, v222, v67, vcc
	v_cmp_lt_i32_e32 vcc, 15, v44
	s_nop 1
	v_cndmask_b32_e32 v68, v222, v68, vcc
	v_cmp_lt_i32_e32 vcc, 16, v44
	s_nop 1
	v_cndmask_b32_e32 v69, v222, v69, vcc
	v_cmp_lt_i32_e32 vcc, 17, v44
	s_nop 1
	v_cndmask_b32_e32 v70, v222, v70, vcc
	v_cmp_lt_i32_e32 vcc, 18, v44
	s_nop 1
	v_cndmask_b32_e32 v71, v222, v71, vcc
	v_cmp_lt_i32_e32 vcc, 31, v44
	s_nop 1
	v_cndmask_b32_e32 v72, v222, v72, vcc
	v_cmp_lt_i32_e32 vcc, 32, v44
	s_nop 1
	v_cndmask_b32_e32 v73, v222, v73, vcc
	v_cmp_lt_i32_e32 vcc, 33, v44
	s_nop 1
	v_cndmask_b32_e32 v74, v222, v74, vcc
	v_cmp_lt_i32_e32 vcc, 34, v44
	s_nop 1
	v_cndmask_b32_e32 v75, v222, v75, vcc
	v_cmp_lt_i32_e32 vcc, 47, v44
	s_nop 1
	v_cndmask_b32_e32 v40, v222, v40, vcc
	v_cmp_lt_i32_e32 vcc, 48, v44
	s_nop 1
	v_cndmask_b32_e32 v41, v222, v41, vcc
	v_cmp_lt_i32_e32 vcc, 49, v44
	s_nop 1
	v_cndmask_b32_e32 v42, v222, v42, vcc
	v_cmp_lt_i32_e32 vcc, 50, v44
	s_nop 1
	v_cndmask_b32_e32 v43, v222, v43, vcc

; #define LAS __attribute__((address_space(3)))
; #define MFMA16(a, b, c) __builtin_amdgcn_mfma_f32_16x16x32_bf16((a), (b), (c), 0, 0, 0)
; __device__ __forceinline__ void sel_group(const LAS bf16_t* Kt, const LAS bf16_t* Vt, LAS float* S, const bf16x8 qB0, const bf16x8 qB1, int jc, int rc, bool valid, bool masked, int tw64, int lr, int q) {
;     LAS float* Srow = S + (jc * 3 + rc) * 68;
;     const float mref = Srow[65]; const bool st = Srow[66] != 0.f;
;     f32x4 acc[4];
; #pragma unroll
;     for (int dt = 0; dt < 4; ++dt) acc[dt] = *(const LAS f32x4*)(Srow + 16 * dt + 4 * q);
;     float lc = Srow[64];
;     const float nm = valid ? -mref : -1e30f;
;     const f32x4 c0 = (f32x4){nm, nm, nm, nm};
;     const LAS bf16_t* kbase = Kt + lr * 72 + 8 * q;
;     f32x4 s[4];
;     {
;         bf16x8 kf[2][2];
;         kf[0][0] = *(const LAS bf16x8*)(kbase); kf[0][1] = *(const LAS bf16x8*)(kbase + 32);
; #pragma unroll
;         for (int mt = 0; mt < 4; ++mt) {
;             if (mt < 3) { kf[(mt + 1) & 1][0] = *(const LAS bf16x8*)(kbase + 16 * (mt + 1) * 72); kf[(mt + 1) & 1][1] = *(const LAS bf16x8*)(kbase + 16 * (mt + 1) * 72 + 32); }
;             __builtin_amdgcn_sched_barrier(0);
;             __builtin_amdgcn_s_setprio(1); s[mt] = MFMA16(kf[mt & 1][0], qB0, c0); s[mt] = MFMA16(kf[mt & 1][1], qB1, s[mt]); __builtin_amdgcn_s_setprio(0);
;             __builtin_amdgcn_sched_barrier(0);
;         }
;     }
;     if (masked) {
;         const int hq = tw64 + jc - 4 * q;
; #pragma unroll
;         for (int mt = 0; mt < 4; ++mt)
; #pragma unroll
;             for (int i = 0; i < 4; ++i) s[mt][i] = ((16 * mt + i) <= hq) ? s[mt][i] : -1e30f;
.LBB0_1092:
	s_cmp_lt_u32 s10, 11
	s_cbranch_scc1 .LBB0_1057
	s_nop 0
	v_mad_u64_u32 v[40:41], s[4:5], v116, 3, v[96:97]
	v_mul_lo_u32 v40, v40, s36
	v_add_u32_e32 v71, s49, v40
	v_add_u32_e32 v40, v71, v97
	ds_read_b96 v[68:70], v71 offset:46336
	ds_read_b128 v[72:75], v117 offset:6912
	ds_read_b128 v[122:125], v117 offset:6976
	ds_read_b128 v[52:55], v40 offset:46080
	ds_read_b128 v[48:51], v40 offset:46144
	ds_read_b128 v[44:47], v40 offset:46208
	ds_read_b128 v[40:43], v40 offset:46272
	s_waitcnt lgkmcnt(6)
	v_cndmask_b32_e64 v76, v222, -v69, s[70:71]
	v_mov_b32_e32 v77, v76
	v_mov_b32_e32 v78, v76
	v_mov_b32_e32 v79, v76
	s_nop 0
	s_nop 0
	v_mfma_f32_16x16x32_bf16 v[56:59], v[174:177], v[32:35], v[76:79]
	v_mfma_f32_16x16x32_bf16 v[56:59], v[178:181], v[36:39], v[56:59]
	v_mfma_f32_16x16x32_bf16 v[60:63], v[182:185], v[32:35], v[76:79]
	v_mfma_f32_16x16x32_bf16 v[60:63], v[186:189], v[36:39], v[60:63]
	v_mfma_f32_16x16x32_bf16 v[64:67], v[200:203], v[32:35], v[76:79]
	v_mfma_f32_16x16x32_bf16 v[64:67], v[216:219], v[36:39], v[64:67]
	s_waitcnt lgkmcnt(5)
	v_mfma_f32_16x16x32_bf16 v[32:35], v[72:75], v[32:35], v[76:79]
	s_waitcnt lgkmcnt(4)
	v_mfma_f32_16x16x32_bf16 v[32:35], v[122:125], v[36:39], v[32:35]
	s_nop 0
	s_and_b64 vcc, exec, s[72:73]
	s_cbranch_vccnz .LBB0_1095
	v_add_u32_e32 v36, v116, v111
	v_cmp_lt_i32_e32 vcc, -1, v36
	s_nop 1
	v_cndmask_b32_e32 v56, v222, v56, vcc
	v_cmp_lt_i32_e32 vcc, 0, v36
	s_nop 1
	v_cndmask_b32_e32 v57, v222, v57, vcc
	v_cmp_lt_i32_e32 vcc, 1, v36
	s_nop 1
	v_cndmask_b32_e32 v58, v222, v58, vcc
	v_cmp_lt_i32_e32 vcc, 2, v36
	s_nop 1
	v_cndmask_b32_e32 v59, v222, v59, vcc
	v_cmp_lt_i32_e32 vcc, 15, v36
	s_nop 1
	v_cndmask_b32_e32 v60, v222, v60, vcc
	v_cmp_lt_i32_e32 vcc, 16, v36
	s_nop 1
	v_cndmask_b32_e32 v61, v222, v61, vcc
	v_cmp_lt_i32_e32 vcc, 17, v36
	s_nop 1
	v_cndmask_b32_e32 v62, v222, v62, vcc
	v_cmp_lt_i32_e32 vcc, 18, v36
	s_nop 1
	v_cndmask_b32_e32 v63, v222, v63, vcc
	v_cmp_lt_i32_e32 vcc, 31, v36
	s_nop 1
	v_cndmask_b32_e32 v64, v222, v64, vcc
	v_cmp_lt_i32_e32 vcc, 32, v36
	s_nop 1
	v_cndmask_b32_e32 v65, v222, v65, vcc
	v_cmp_lt_i32_e32 vcc, 33, v36
	s_nop 1
	v_cndmask_b32_e32 v66, v222, v66, vcc
	v_cmp_lt_i32_e32 vcc, 34, v36
	s_nop 1
	v_cndmask_b32_e32 v67, v222, v67, vcc
	v_cmp_lt_i32_e32 vcc, 47, v36
	s_nop 1
	v_cndmask_b32_e32 v32, v222, v32, vcc
	v_cmp_lt_i32_e32 vcc, 48, v36
	s_nop 1
	v_cndmask_b32_e32 v33, v222, v33, vcc
	v_cmp_lt_i32_e32 vcc, 49, v36
	s_nop 1
	v_cndmask_b32_e32 v34, v222, v34, vcc
	v_cmp_lt_i32_e32 vcc, 50, v36
	s_nop 1
	v_cndmask_b32_e32 v35, v222, v35, vcc

; __device__ __forceinline__ void xcd_barrier(const XcdBarrier& b) {
;     asm volatile("s_waitcnt vmcnt(0)" ::: "memory");
;     __syncthreads();
;     if (threadIdx.x == 0) {
;         unsigned* bar = b.bar;
;         __builtin_amdgcn_s_waitcnt(0);
;         unsigned nloc = b.st[0], nx = b.st[1];
;         if (nloc == 0u) { xcd_barrier_complete(bar, b.x, nloc, nx); b.st[0] = nloc; b.st[1] = nx; }
.LBB0_1110:
	s_setprio 0
	v_readlane_b32 s61, v255, 24
	v_readlane_b32 s64, v253, 9
	s_add_i32 s17, s61, 4
	v_readlane_b32 s65, v253, 10
	s_cmp_ge_i32 s17, s65
	s_cbranch_scc1 .LBB0_1123
	v_readlane_b32 s4, v253, 19
	v_readlane_b32 s5, v253, 20
	v_readlane_b32 s34, v253, 7
	s_mov_b64 s[2:3], -1
	s_and_b64 vcc, exec, s[4:5]
	v_readlane_b32 s35, v253, 8
	v_readlane_b32 s38, v255, 21
	s_cbranch_vccz .LBB0_1166
	s_waitcnt vmcnt(0)
	s_waitcnt lgkmcnt(0)
	s_barrier
	s_mov_b64 s[2:3], exec
	v_readlane_b32 s4, v253, 0
	v_readlane_b32 s5, v253, 1
	s_and_b64 s[4:5], s[2:3], s[4:5]
	s_mov_b64 exec, s[4:5]
	s_cbranch_execz .LBB0_1165
	v_readlane_b32 s4, v254, 40
	s_waitcnt vmcnt(0) expcnt(0) lgkmcnt(0)
	s_nop 0
	v_mov_b32_e32 v0, s4
	ds_read_b32 v2, v0
	v_readlane_b32 s4, v254, 41
	s_waitcnt lgkmcnt(0)
	v_cmp_ne_u32_e32 vcc, 0, v2
	v_mov_b32_e32 v0, s4
	ds_read_b32 v0, v0
	s_cbranch_vccnz .LBB0_1129
	v_readlane_b32 s6, v253, 3
	v_readlane_b32 s7, v253, 4
	s_load_dwordx2 s[4:5], s[6:7], 0x4
	s_mov_b32 s11, 1
	s_waitcnt lgkmcnt(0)
	s_mul_i32 s10, s4, s82
	s_mul_i32 s10, s10, s5
	s_branch .LBB0_1116
